# on top of previous: NSA item setup loads compressed K/V in one batch (20 loads in flight, K as dwordx4 + ds_write_b64); wave OR for the block-selection mask via DPP instead of a 64-iteration scalar lo
# speedup vs baseline: 1.0087x; 1.0006x over previous
; DI bf16_t f2bf(float f) { return (bf16_t)(pack2(f, 0.f) & 0xFFFFu); }
; #define MFMA32(a, b, c) __builtin_amdgcn_mfma_f32_32x32x16_bf16((a), (b), (c), 0, 0, 0)
; __device__ __forceinline__ void rwkv_chunked(unsigned char* smem, CP p, int L, int b, int h) {
;     ...
;         { float ev[16];
; #pragma unroll
;           for (int j = 0; j < 16; ++j) ev[j] = EW[j * 64 + c];
; #pragma unroll
;           for (int i = 0; i < 2; ++i) { const int t = wv * 2 + i; float cum = 0.f;
; #pragma unroll
;             for (int j = 0; j < 16; ++j) cum += (j <= t) ? ev[j] : 0.f;
;             const float Pt = __expf(-cum), Pm = __expf(-(cum - ew_[i])), iP = __expf(cum);
;             const float al = -nk_[i] * Pm, rh = r_[i] * Pt, be = ab_[i] * iP, ka = kx_[i] * iP;
;             AR[t * 72 + c] = f2bf(al); AR[(16 + t) * 72 + c] = f2bf(rh); BKr[t * 72 + c] = f2bf(be); BKr[(16 + t) * 72 + c] = f2bf(ka);
;             BKt[c * 40 + t] = f2bf(be); BKt[c * 40 + 16 + t] = f2bf(ka);
;             UV[c * 40 + 16 + t] = f2bf(v_[i]); VS[t * 64 + c] = v_[i];
;             if (t == 15) PC[c] = Pt; } }
;     ...
;         } else if (wv < 3) {
;             const int vb = wv - 1;
; #pragma unroll
;             for (int s = 0; s < 4; ++s) acc = MFMA32(*(const bf16x8*)(ZB + (32 * vb + qi) * 72 + 16 * s + 8 * hl), *(const bf16x8*)(AR + qi * 72 + 16 * s + 8 * hl), acc);
;         }
.LBB0_669:
	v_add_f32_e32 v13, v13, v14
	v_max_f32_e32 v13, 0x179abe15, v13
	v_add_f32_e32 v14, v32, v33
	v_rsq_f32_e32 v13, v13
	v_max_f32_e32 v14, 0x179abe15, v14
	v_rsq_f32_e32 v14, v14
	v_lshlrev_b32_e32 v11, 16, v11
	v_lshlrev_b32_e32 v44, 16, v0
	v_lshlrev_b32_e32 v3, 16, v3
	v_sub_f32_e32 v0, v11, v44
	v_mul_f32_e32 v13, v10, v13
	v_sub_f32_e32 v10, v44, v3
	v_fmac_f32_e32 v44, v64, v0
	v_fmac_f32_e32 v3, v64, v10
	v_mul_f32_e32 v45, v15, v14
	ds_read2st64_b32 v[10:11], v76 offset0:106 offset1:107
	ds_read2st64_b32 v[14:15], v76 offset0:108 offset1:109
	ds_read2st64_b32 v[32:33], v76 offset0:110 offset1:111
	ds_read2st64_b32 v[34:35], v76 offset0:112 offset1:113
	ds_read2st64_b32 v[36:37], v76 offset0:114 offset1:115
	ds_read2st64_b32 v[38:39], v76 offset0:116 offset1:117
	ds_read2st64_b32 v[40:41], v76 offset0:118 offset1:119
	ds_read2st64_b32 v[42:43], v76 offset0:120 offset1:121
	s_waitcnt lgkmcnt(7)
	v_add_f32_e32 v0, 0, v10
	v_cndmask_b32_e64 v0, v0, 0, s[58:59]
	v_cndmask_b32_e64 v10, v11, 0, s[60:61]
	v_add_f32_e32 v10, v0, v10
	s_waitcnt lgkmcnt(6)
	v_cndmask_b32_e64 v46, v14, 0, s[60:61]
	v_add_f32_e32 v10, v10, v46
	v_cndmask_b32_e64 v46, v15, 0, s[62:63]
	v_add_f32_e32 v10, v10, v46
	s_waitcnt lgkmcnt(5)
	v_cndmask_b32_e64 v46, v32, 0, s[62:63]
	v_add_f32_e32 v10, v10, v46
	v_cndmask_b32_e64 v46, v33, 0, s[54:55]
	v_add_f32_e32 v10, v10, v46
	s_waitcnt lgkmcnt(4)
	v_cndmask_b32_e64 v46, v34, 0, s[54:55]
	v_add_f32_e32 v10, v10, v46
	v_cndmask_b32_e64 v46, v35, 0, s[64:65]
	v_add_f32_e32 v10, v10, v46
	s_waitcnt lgkmcnt(3)
	v_cndmask_b32_e64 v46, v36, 0, s[64:65]
	v_add_f32_e32 v10, v10, v46
	v_cndmask_b32_e64 v46, v37, 0, s[66:67]
	v_add_f32_e32 v10, v10, v46
	s_waitcnt lgkmcnt(2)
	v_cndmask_b32_e64 v46, v38, 0, s[66:67]
	v_add_f32_e32 v10, v10, v46
	v_cndmask_b32_e64 v46, v39, 0, s[68:69]
	v_add_f32_e32 v10, v10, v46
	s_waitcnt lgkmcnt(1)
	v_cndmask_b32_e64 v46, v40, 0, s[68:69]
	v_add_f32_e32 v10, v10, v46
	v_cndmask_b32_e64 v46, v41, 0, s[70:71]
	v_add_f32_e32 v10, v10, v46
	s_waitcnt lgkmcnt(0)
	v_cndmask_b32_e64 v46, v42, 0, s[70:71]
	v_add_f32_e32 v10, v10, v46
	v_cndmask_b32_e64 v46, v43, 0, s[72:73]
	v_add_f32_e32 v10, v10, v46
	v_mov_b32_e32 v114, v10
	v_sub_f32_e32 v5, v10, v5
	v_mul_f32_e32 v46, 0xbfb8aa3b, v10
	v_mul_f32_e32 v5, 0xbfb8aa3b, v5
	v_exp_f32_e32 v46, v46
	v_exp_f32_e32 v5, v5
	v_mul_f32_e32 v10, 0x3fb8aa3b, v10
	v_exp_f32_e32 v10, v10
	v_mul_f32_e32 v9, v9, v13
	v_mul_f32_e64 v5, v5, -v13
	v_mul_f32_e32 v4, v4, v46
	v_mul_f32_e32 v9, v9, v10
	v_mul_f32_e32 v7, v7, v10
	v_cvt_pk_bf16_f32 v5, v5, s0
	v_cvt_pk_bf16_f32 v4, v4, s0
	ds_write_b16 v92, v5 offset:9216
	ds_write_b16 v92, v4 offset:11520
	v_cvt_pk_bf16_f32 v4, v9, s0
	v_cvt_pk_bf16_f32 v5, v7, s0
	ds_write_b16 v92, v4 offset:31232
	ds_write_b16 v92, v5 offset:33536
	ds_write_b16 v94, v4 offset:13824
	ds_write_b16 v95, v5 offset:13856
	v_add_f32_e32 v5, v114, v6
	v_sub_f32_e32 v6, v5, v6
	v_mul_f32_e32 v0, 0xbfb8aa3b, v5
	v_mul_f32_e32 v6, 0xbfb8aa3b, v6
	v_exp_f32_e32 v0, v0
	v_exp_f32_e32 v6, v6
	v_mul_f32_e32 v5, 0x3fb8aa3b, v5
	v_exp_f32_e32 v5, v5
	v_cvt_pk_bf16_f32 v4, v44, s0
	ds_write_b16 v95, v4 offset:18976
	v_add_u32_e32 v4, v77, v90
	v_mul_f32_e32 v12, v12, v45
	ds_write_b32 v4, v44 offset:61312
	v_mul_f32_e64 v4, v6, -v45
	v_mul_f32_e32 v2, v2, v0
	v_mul_f32_e32 v6, v12, v5
	v_mul_f32_e32 v5, v8, v5
	v_cvt_pk_bf16_f32 v4, v4, s0
	v_cvt_pk_bf16_f32 v2, v2, s0
	ds_write_b16 v96, v4 offset:9216
	ds_write_b16 v96, v2 offset:11520
	v_cvt_pk_bf16_f32 v2, v6, s0
	v_cvt_pk_bf16_f32 v4, v5, s0
	ds_write_b16 v96, v2 offset:31232
	ds_write_b16 v96, v4 offset:33536
	ds_write_b16 v94, v2 offset:13826
	ds_write_b16 v97, v4 offset:13856
	v_cvt_pk_bf16_f32 v2, v3, s0
	ds_write_b16 v97, v2 offset:18976
	v_add_u32_e32 v2, v77, v98
	ds_write_b32 v2, v3 offset:61312
	s_and_saveexec_b64 s[16:17], s[8:9]
	ds_write_b32 v77, v0 offset:65408
	s_or_b64 exec, exec, s[16:17]
	s_waitcnt lgkmcnt(0)
	s_barrier
	s_and_saveexec_b64 s[16:17], s[48:49]
	s_xor_b64 vcc, exec, s[16:17]
	s_cbranch_execz .LBB0_675
	v_mov_b32_e32 v14, v1
	v_mov_b32_e32 v15, v1
	v_mov_b32_e32 v0, v1
	v_mov_b32_e32 v2, v1
	v_mov_b32_e32 v3, v1
	v_mov_b32_e32 v4, v1
	v_mov_b32_e32 v5, v1
	v_mov_b32_e32 v6, v1
	v_mov_b32_e32 v7, v1
	v_mov_b32_e32 v8, v1
	v_mov_b32_e32 v9, v1
	v_mov_b32_e32 v10, v1
	v_mov_b32_e32 v11, v1
	v_mov_b32_e32 v12, v1
	v_mov_b32_e32 v13, v1
	v_mov_b64_e32 v[46:47], v[14:15]
	v_mov_b64_e32 v[44:45], v[12:13]
	v_mov_b64_e32 v[42:43], v[10:11]
	v_mov_b64_e32 v[40:41], v[8:9]
	v_mov_b64_e32 v[38:39], v[6:7]
	v_mov_b64_e32 v[36:37], v[4:5]
	v_mov_b64_e32 v[34:35], v[2:3]
	v_mov_b64_e32 v[32:33], v[0:1]
	s_and_saveexec_b64 s[16:17], s[54:55]
	s_cbranch_execz .LBB0_674
	ds_read_b128 v[2:5], v79
	ds_read_b128 v[6:9], v80 offset:9216
	s_waitcnt lgkmcnt(0)
	v_mfma_f32_32x32x16_bf16 v[32:47], v[2:5], v[6:9], 0
	ds_read_b128 v[2:5], v79 offset:32
	ds_read_b128 v[6:9], v80 offset:9248
	s_waitcnt lgkmcnt(0)
	v_mfma_f32_32x32x16_bf16 v[32:47], v[2:5], v[6:9], v[32:47]
	ds_read_b128 v[2:5], v79 offset:64
	ds_read_b128 v[6:9], v80 offset:9280
	s_waitcnt lgkmcnt(0)
	v_mfma_f32_32x32x16_bf16 v[32:47], v[2:5], v[6:9], v[32:47]
	ds_read_b128 v[2:5], v79 offset:96
	ds_read_b128 v[6:9], v80 offset:9312
	s_waitcnt lgkmcnt(0)
	v_mfma_f32_32x32x16_bf16 v[32:47], v[2:5], v[6:9], v[32:47]

; DI bf16_t f2bf(float f) { return (bf16_t)(pack2(f, 0.f) & 0xFFFFu); }
; __device__ __forceinline__ void nsa_item(unsigned char* smem, CP p, int L, int b, int g, int qb, int ocol) {
;     ...
;     if (tid == 0) *ORM = 0u;
;     if (tid < 64) SELM[tid] = 0u;
;     if (tid < 256) PBv[tid * 32] = 0.f;
;     { const float* kc = (const float*)(p->ws + WS_KC) + ((size_t)(0 * 16 + b) * 2 + g) * 128 * 64; const float* vc = (const float*)(p->ws + WS_KC) + ((size_t)(1 * 16 + b) * 2 + g) * 128 * 64;
;       for (int i = tid; i < 128 * 64; i += 512) { const int n = i >> 6, d = i & 63; KT2[n * KTS + d] = f2bf(kc[i]); }
;       for (int i = tid; i < 128 * 64; i += 512) { const int n = i & 127, d = i >> 7; VT2[d * 136 + n] = f2bf(vc[n * 64 + d]); } }
.LBB0_724:
	s_or_b64 exec, exec, s[4:5]
	v_cmp_eq_u32_e32 vcc, 0, v74
	s_and_saveexec_b64 s[0:1], vcc
	ds_write_b32 v1, v1 offset:20992
	s_or_b64 exec, exec, s[0:1]
	v_cmp_gt_i32_e32 vcc, 64, v74
	s_and_saveexec_b64 s[0:1], vcc
	v_lshl_add_u32 v0, v74, 2, 0
	ds_write_b32 v0, v1 offset:20736
	s_or_b64 exec, exec, s[0:1]
	s_movk_i32 s0, 0x100
	v_cmp_gt_i32_e32 vcc, s0, v74
	s_and_saveexec_b64 s[0:1], vcc
	v_lshl_add_u32 v0, v74, 7, 0
	ds_write_b32 v0, v1 offset:54272
	s_or_b64 exec, exec, s[0:1]
	s_movk_i32 s0, 0x2000
	v_bfe_u32 v7, v130, 1, 4
	v_and_b32_e32 v96, 63, v74
	v_cmp_gt_i32_e32 vcc, s0, v74
	s_and_saveexec_b64 s[4:5], vcc
	s_cbranch_execz .LBB0_745
	v_readlane_b32 s0, v254, 14
	v_readlane_b32 s1, v254, 15
	v_lshlrev_b32_e32 v0, 16, v7
	v_lshl_or_b32 v0, v77, 15, v0
	v_lshl_add_u32 v3, v74, 4, v0
	v_and_b32_e32 v4, 0x7f, v74
	v_lshrrev_b32_e32 v5, 7, v74
	v_lshl_add_u32 v6, v4, 6, v5
	v_lshl_add_u32 v6, v6, 2, v0
	v_add_u32_e32 v6, 0x100000, v6
	global_load_dwordx4 v[8:11], v3, s[30:31]
	v_add_u32_e32 v40, 0x2000, v3
	global_load_dwordx4 v[12:15], v40, s[30:31]
	v_add_u32_e32 v41, 0x4000, v3
	global_load_dwordx4 v[16:19], v41, s[30:31]
	v_add_u32_e32 v42, 0x6000, v3
	global_load_dwordx4 v[20:23], v42, s[30:31]
	global_load_dword v24, v6, s[30:31]
	global_load_dword v25, v6, s[30:31] offset:16
	global_load_dword v26, v6, s[30:31] offset:32
	global_load_dword v27, v6, s[30:31] offset:48
	global_load_dword v28, v6, s[30:31] offset:64
	global_load_dword v29, v6, s[30:31] offset:80
	global_load_dword v30, v6, s[30:31] offset:96
	global_load_dword v31, v6, s[30:31] offset:112
	global_load_dword v32, v6, s[30:31] offset:128
	global_load_dword v33, v6, s[30:31] offset:144
	global_load_dword v34, v6, s[30:31] offset:160
	global_load_dword v35, v6, s[30:31] offset:176
	global_load_dword v36, v6, s[30:31] offset:192
	global_load_dword v37, v6, s[30:31] offset:208
	global_load_dword v38, v6, s[30:31] offset:224
	global_load_dword v39, v6, s[30:31] offset:240
	v_lshrrev_b32_e32 v43, 4, v74
	v_and_b32_e32 v44, 15, v74
	v_mul_u32_u24_e32 v43, 0x90, v43
	v_lshl_add_u32 v43, v44, 3, v43
	v_add_u32_e32 v43, s0, v43
	v_mul_u32_u24_e32 v45, 0x110, v5
	v_lshl_add_u32 v45, v4, 1, v45
	v_add_u32_e32 v45, s1, v45
	s_waitcnt vmcnt(16)
	v_cvt_pk_bf16_f32 v46, v8, v9
	v_cvt_pk_bf16_f32 v47, v10, v11
	ds_write_b64 v43, v[46:47]
	v_cvt_pk_bf16_f32 v48, v12, v13
	v_cvt_pk_bf16_f32 v49, v14, v15
	ds_write_b64 v43, v[48:49] offset:4608
	v_cvt_pk_bf16_f32 v50, v16, v17
	v_cvt_pk_bf16_f32 v51, v18, v19
	ds_write_b64 v43, v[50:51] offset:9216
	v_cvt_pk_bf16_f32 v52, v20, v21
	v_cvt_pk_bf16_f32 v53, v22, v23
	ds_write_b64 v43, v[52:53] offset:13824
	s_waitcnt vmcnt(0)
	v_cvt_pk_bf16_f32 v54, v24, v25
	ds_write_b16 v45, v54
	ds_write_b16_d16_hi v45, v54 offset:1088
	v_cvt_pk_bf16_f32 v55, v26, v27
	ds_write_b16 v45, v55 offset:2176
	ds_write_b16_d16_hi v45, v55 offset:3264
	v_cvt_pk_bf16_f32 v56, v28, v29
	ds_write_b16 v45, v56 offset:4352
	ds_write_b16_d16_hi v45, v56 offset:5440
	v_cvt_pk_bf16_f32 v57, v30, v31
	ds_write_b16 v45, v57 offset:6528
	ds_write_b16_d16_hi v45, v57 offset:7616
	v_cvt_pk_bf16_f32 v58, v32, v33
	ds_write_b16 v45, v58 offset:8704
	ds_write_b16_d16_hi v45, v58 offset:9792
	v_cvt_pk_bf16_f32 v59, v34, v35
	ds_write_b16 v45, v59 offset:10880
	ds_write_b16_d16_hi v45, v59 offset:11968
	v_cvt_pk_bf16_f32 v60, v36, v37
	ds_write_b16 v45, v60 offset:13056
	ds_write_b16_d16_hi v45, v60 offset:14144
	v_cvt_pk_bf16_f32 v61, v38, v39
	ds_write_b16 v45, v61 offset:15232
	ds_write_b16_d16_hi v45, v61 offset:16320

; __device__ __forceinline__ void nsa_item(unsigned char* smem, CP p, int L, int b, int g, int qb, int ocol) {
;     ...
;         const int q = tid & 63, part = tid >> 6, cur = qb;
; #pragma unroll
;         for (int mm = 0; mm < 4; ++mm) { const int m = part * 4 + mm; float v;
;             if (m == 0 || m == cur || m == cur - 1) v = INFINITY;
;             else if (m <= cur) { v = 0.f; for (int h2 = 0; h2 < 4; ++h2) v += PA[(h2 * 64 + q) * 32 + m] + PBv[(h2 * 64 + q) * 32 + m]; }
;             else v = -INFINITY;
;             IMP[q * 33 + m] = v; }
;         __syncthreads();
;         unsigned bits = 0u;
; #pragma unroll
;         for (int mm = 0; mm < 4; ++mm) { const int m = part * 4 + mm; const float v = IMP[q * 33 + m]; int rank = 0;
;             for (int m2 = 0; m2 < 32; ++m2) { const float v2 = IMP[q * 33 + m2]; rank += (v2 > v || (v2 == v && m2 < m)) ? 1 : 0; }
;             if (rank < 8 && v > -INFINITY) bits |= 1u << m; }
.LBB0_767:
	s_or_b64 exec, exec, s[0:1]
	s_waitcnt vmcnt(1)
	v_lshlrev_b32_e32 v34, 16, v76
	v_mul_f32_e32 v34, 0xbfb8aa3b, v34
	v_exp_f32_e32 v34, v34
	ds_write_b32 v73, v37 offset:12
	s_waitcnt lgkmcnt(0)
	s_barrier
	v_add_f32_e32 v34, 1.0, v34
	ds_read2_b32 v[66:67], v73 offset1:1
	ds_read2_b32 v[50:51], v36 offset1:1
	v_rcp_f32_e32 v69, v34
	v_and_b32_e32 v34, 0xffff0000, v76
	v_mul_f32_e32 v34, 0xbfb8aa3b, v34
	v_exp_f32_e32 v34, v34
	s_waitcnt lgkmcnt(0)
	v_cmp_eq_f32_e64 s[4:5], v50, v66
	v_cmp_lt_i32_e32 vcc, 0, v94
	ds_read2_b32 v[60:61], v36 offset0:2 offset1:3
	ds_read2_b32 v[62:63], v36 offset0:4 offset1:5
	ds_read2_b32 v[64:65], v36 offset0:6 offset1:7
	ds_read2_b32 v[56:57], v36 offset0:8 offset1:9
	v_cmp_gt_f32_e64 s[0:1], v50, v66
	s_and_b64 s[4:5], vcc, s[4:5]
	v_add_f32_e32 v34, 1.0, v34
	s_or_b64 s[0:1], s[0:1], s[4:5]
	v_cmp_eq_f32_e64 s[4:5], v51, v66
	v_rcp_f32_e32 v136, v34
	v_cndmask_b32_e64 v34, 0, 1, s[0:1]
	v_cmp_gt_f32_e64 s[0:1], v51, v66
	s_and_b64 s[4:5], vcc, s[4:5]
	s_or_b64 s[0:1], s[0:1], s[4:5]
	v_addc_co_u32_e64 v34, s[0:1], 0, v34, s[0:1]
	s_waitcnt lgkmcnt(3)
	v_cmp_eq_f32_e64 s[4:5], v60, v66
	v_cmp_gt_f32_e64 s[0:1], v60, v66
	s_and_b64 s[4:5], vcc, s[4:5]
	s_or_b64 s[0:1], s[0:1], s[4:5]
	v_cmp_eq_f32_e64 s[4:5], v61, v66
	v_cndmask_b32_e64 v35, 0, 1, s[0:1]
	v_cmp_gt_f32_e64 s[0:1], v61, v66
	s_and_b64 s[4:5], vcc, s[4:5]
	s_or_b64 s[0:1], s[0:1], s[4:5]
	v_addc_co_u32_e64 v34, s[0:1], v34, v35, s[0:1]
	s_waitcnt lgkmcnt(2)
	v_cmp_eq_f32_e64 s[6:7], v62, v66
	v_cmp_lt_i32_e64 s[0:1], 1, v94
	v_cmp_gt_f32_e64 s[4:5], v62, v66
	s_and_b64 s[6:7], s[0:1], s[6:7]
	s_or_b64 s[4:5], s[4:5], s[6:7]
	v_cmp_eq_f32_e64 s[6:7], v63, v66
	v_cndmask_b32_e64 v35, 0, 1, s[4:5]
	v_cmp_gt_f32_e64 s[4:5], v63, v66
	s_and_b64 s[6:7], s[0:1], s[6:7]
	s_or_b64 s[4:5], s[4:5], s[6:7]
	v_addc_co_u32_e64 v34, s[4:5], v34, v35, s[4:5]
	s_waitcnt lgkmcnt(1)
	v_cmp_eq_f32_e64 s[6:7], v64, v66
	v_cmp_gt_f32_e64 s[4:5], v64, v66
	s_and_b64 s[6:7], s[0:1], s[6:7]
	s_or_b64 s[4:5], s[4:5], s[6:7]
	v_cmp_eq_f32_e64 s[6:7], v65, v66
	v_cndmask_b32_e64 v35, 0, 1, s[4:5]
	v_cmp_gt_f32_e64 s[4:5], v65, v66
	s_and_b64 s[6:7], s[0:1], s[6:7]
	s_or_b64 s[4:5], s[4:5], s[6:7]
	v_addc_co_u32_e64 v34, s[4:5], v34, v35, s[4:5]
	s_waitcnt lgkmcnt(0)
	v_cmp_eq_f32_e64 s[6:7], v56, v66
	v_cmp_lt_i32_e64 s[16:17], 2, v94
	ds_read2_b32 v[58:59], v36 offset0:10 offset1:11
	ds_read2_b32 v[52:53], v36 offset0:12 offset1:13
	ds_read2_b32 v[54:55], v36 offset0:14 offset1:15
	ds_read2_b32 v[46:47], v36 offset0:16 offset1:17
	v_cmp_gt_f32_e64 s[4:5], v56, v66
	s_and_b64 s[6:7], s[16:17], s[6:7]
	s_or_b64 s[4:5], s[4:5], s[6:7]
	v_cmp_eq_f32_e64 s[6:7], v57, v66
	v_cndmask_b32_e64 v35, 0, 1, s[4:5]
	v_cmp_gt_f32_e64 s[4:5], v57, v66
	s_and_b64 s[6:7], s[16:17], s[6:7]
	s_or_b64 s[4:5], s[4:5], s[6:7]
	v_addc_co_u32_e64 v34, s[4:5], v34, v35, s[4:5]
	s_waitcnt lgkmcnt(3)
	v_cmp_eq_f32_e64 s[6:7], v58, v66
	v_cmp_gt_f32_e64 s[4:5], v58, v66
	s_and_b64 s[6:7], s[16:17], s[6:7]
	s_or_b64 s[4:5], s[4:5], s[6:7]
	v_cmp_eq_f32_e64 s[6:7], v59, v66
	v_cndmask_b32_e64 v35, 0, 1, s[4:5]
	v_cmp_gt_f32_e64 s[4:5], v59, v66
	s_and_b64 s[6:7], s[16:17], s[6:7]
	s_or_b64 s[4:5], s[4:5], s[6:7]
	v_addc_co_u32_e64 v34, s[4:5], v34, v35, s[4:5]
	s_waitcnt lgkmcnt(2)
	v_cmp_eq_f32_e64 s[8:9], v52, v66
	v_cmp_lt_i32_e64 s[4:5], 3, v94
	v_cmp_gt_f32_e64 s[6:7], v52, v66
	s_and_b64 s[8:9], s[4:5], s[8:9]
	s_or_b64 s[6:7], s[6:7], s[8:9]
	v_cmp_eq_f32_e64 s[8:9], v53, v66
	v_cndmask_b32_e64 v35, 0, 1, s[6:7]
	v_cmp_gt_f32_e64 s[6:7], v53, v66
	s_and_b64 s[8:9], s[4:5], s[8:9]
	s_or_b64 s[6:7], s[6:7], s[8:9]
	v_addc_co_u32_e64 v34, s[6:7], v34, v35, s[6:7]
	s_waitcnt lgkmcnt(1)
	v_cmp_eq_f32_e64 s[8:9], v54, v66
	v_cmp_gt_f32_e64 s[6:7], v54, v66
	s_and_b64 s[8:9], s[4:5], s[8:9]
	s_or_b64 s[6:7], s[6:7], s[8:9]
	v_cmp_eq_f32_e64 s[8:9], v55, v66
	v_cndmask_b32_e64 v35, 0, 1, s[6:7]
	v_cmp_gt_f32_e64 s[6:7], v55, v66
	s_and_b64 s[8:9], s[4:5], s[8:9]
	s_or_b64 s[6:7], s[6:7], s[8:9]
	v_addc_co_u32_e64 v34, s[6:7], v34, v35, s[6:7]
	s_waitcnt lgkmcnt(0)
	v_cmp_eq_f32_e64 s[10:11], v46, v66
	v_cmp_lt_i32_e64 s[6:7], 4, v94
	ds_read2_b32 v[48:49], v36 offset0:18 offset1:19
	ds_read2_b32 v[42:43], v36 offset0:20 offset1:21
	ds_read2_b32 v[44:45], v36 offset0:22 offset1:23
	ds_read2_b32 v[38:39], v36 offset0:24 offset1:25
	v_cmp_gt_f32_e64 s[8:9], v46, v66
	s_and_b64 s[10:11], s[6:7], s[10:11]
	s_or_b64 s[8:9], s[8:9], s[10:11]
	v_cmp_eq_f32_e64 s[10:11], v47, v66
	v_cndmask_b32_e64 v35, 0, 1, s[8:9]
	v_cmp_gt_f32_e64 s[8:9], v47, v66
	s_and_b64 s[10:11], s[6:7], s[10:11]
	s_or_b64 s[8:9], s[8:9], s[10:11]
	v_addc_co_u32_e64 v34, s[8:9], v34, v35, s[8:9]
	s_waitcnt lgkmcnt(3)
	v_cmp_eq_f32_e64 s[10:11], v48, v66
	v_cmp_gt_f32_e64 s[8:9], v48, v66
	s_and_b64 s[10:11], s[6:7], s[10:11]
	s_or_b64 s[8:9], s[8:9], s[10:11]
	v_cmp_eq_f32_e64 s[10:11], v49, v66
	v_cndmask_b32_e64 v35, 0, 1, s[8:9]
	v_cmp_gt_f32_e64 s[8:9], v49, v66
	s_and_b64 s[10:11], s[6:7], s[10:11]
	s_or_b64 s[8:9], s[8:9], s[10:11]
	v_addc_co_u32_e64 v34, s[8:9], v34, v35, s[8:9]
	s_waitcnt lgkmcnt(2)
	v_cmp_eq_f32_e64 s[12:13], v42, v66
	v_cmp_lt_i32_e64 s[8:9], 5, v94
	v_cmp_gt_f32_e64 s[10:11], v42, v66
	s_and_b64 s[12:13], s[8:9], s[12:13]
	s_or_b64 s[10:11], s[10:11], s[12:13]
	v_cmp_eq_f32_e64 s[12:13], v43, v66
	v_cndmask_b32_e64 v35, 0, 1, s[10:11]
	v_cmp_gt_f32_e64 s[10:11], v43, v66
	s_and_b64 s[12:13], s[8:9], s[12:13]
	s_or_b64 s[10:11], s[10:11], s[12:13]
	v_addc_co_u32_e64 v34, s[10:11], v34, v35, s[10:11]
	s_waitcnt lgkmcnt(1)
; __device__ __forceinline__ void nsa_item(unsigned char* smem, CP p, int L, int b, int g, int qb, int ocol) {
;     ...
;         for (int mm = 0; mm < 4; ++mm) { const int m = part * 4 + mm; const float v = IMP[q * 33 + m]; int rank = 0;
;             for (int m2 = 0; m2 < 32; ++m2) { const float v2 = IMP[q * 33 + m2]; rank += (v2 > v || (v2 == v && m2 < m)) ? 1 : 0; }
;             if (rank < 8 && v > -INFINITY) bits |= 1u << m; }
	v_cmp_eq_f32_e64 s[12:13], v44, v66
	v_cmp_gt_f32_e64 s[10:11], v44, v66
	s_and_b64 s[12:13], s[8:9], s[12:13]
	s_or_b64 s[10:11], s[10:11], s[12:13]
	v_cmp_eq_f32_e64 s[12:13], v45, v66
	v_cndmask_b32_e64 v35, 0, 1, s[10:11]
	v_cmp_gt_f32_e64 s[10:11], v45, v66
	s_and_b64 s[12:13], s[8:9], s[12:13]
	s_or_b64 s[10:11], s[10:11], s[12:13]
	v_addc_co_u32_e64 v34, s[10:11], v34, v35, s[10:11]
	s_waitcnt lgkmcnt(0)
	v_cmp_eq_f32_e64 s[14:15], v38, v66
	v_cmp_lt_i32_e64 s[10:11], 6, v94
	ds_read2_b32 v[40:41], v36 offset0:26 offset1:27
	v_cmp_gt_f32_e64 s[12:13], v38, v66
	s_and_b64 s[14:15], s[10:11], s[14:15]
	s_or_b64 s[12:13], s[12:13], s[14:15]
	v_cmp_eq_f32_e64 s[14:15], v39, v66
	v_cndmask_b32_e64 v35, 0, 1, s[12:13]
	v_cmp_gt_f32_e64 s[12:13], v39, v66
	s_and_b64 s[14:15], s[10:11], s[14:15]
	s_or_b64 s[12:13], s[12:13], s[14:15]
	v_addc_co_u32_e64 v34, s[12:13], v34, v35, s[12:13]
	s_waitcnt lgkmcnt(0)
	v_cmp_eq_f32_e64 s[14:15], v40, v66
	v_cmp_gt_f32_e64 s[12:13], v40, v66
	s_and_b64 s[14:15], s[10:11], s[14:15]
	s_or_b64 s[12:13], s[12:13], s[14:15]
	v_cmp_eq_f32_e64 s[14:15], v41, v66
	v_cndmask_b32_e64 v35, 0, 1, s[12:13]
	v_cmp_gt_f32_e64 s[12:13], v41, v66
	s_and_b64 s[14:15], s[10:11], s[14:15]
	s_or_b64 s[12:13], s[12:13], s[14:15]
	v_addc_co_u32_e64 v37, s[12:13], v34, v35, s[12:13]
	ds_read2_b32 v[34:35], v36 offset0:28 offset1:29
	v_cmp_lt_i32_e64 s[12:13], 7, v94
	s_mov_b32 s39, 0xff800000
	v_cmp_eq_f32_e64 s[20:21], v50, v67
	v_cmp_eq_f32_e64 s[22:23], v51, v67
	s_waitcnt lgkmcnt(0)
	v_cmp_eq_f32_e64 s[18:19], v34, v66
	v_cmp_gt_f32_e64 s[14:15], v34, v66
	s_and_b64 s[18:19], s[12:13], s[18:19]
	s_or_b64 s[14:15], s[14:15], s[18:19]
	v_cmp_eq_f32_e64 s[18:19], v35, v66
	v_cndmask_b32_e64 v74, 0, 1, s[14:15]
	v_cmp_gt_f32_e64 s[14:15], v35, v66
	s_and_b64 s[18:19], s[12:13], s[18:19]
	s_or_b64 s[14:15], s[14:15], s[18:19]
	v_addc_co_u32_e64 v74, s[14:15], v37, v74, s[14:15]
	ds_read2_b32 v[36:37], v36 offset0:30 offset1:31
	s_and_b64 s[22:23], vcc, s[22:23]
	s_mov_b32 s38, 0
	s_waitcnt lgkmcnt(0)
	v_cmp_eq_f32_e64 s[18:19], v36, v66
	v_cmp_gt_f32_e64 s[14:15], v36, v66
	s_and_b64 s[18:19], s[12:13], s[18:19]
	s_or_b64 s[14:15], s[14:15], s[18:19]
	v_cmp_eq_f32_e64 s[18:19], v37, v66
	v_cndmask_b32_e64 v76, 0, 1, s[14:15]
	v_cmp_gt_f32_e64 s[14:15], v37, v66
	s_and_b64 s[18:19], s[12:13], s[18:19]
	s_or_b64 s[14:15], s[14:15], s[18:19]
	v_addc_co_u32_e64 v74, s[14:15], v74, v76, s[14:15]
	v_cmp_gt_u32_e64 s[14:15], 8, v74
	v_cmp_lg_f32_e64 s[18:19], s39, v66
	s_and_b64 s[14:15], s[14:15], s[18:19]
	v_lshlrev_b32_e64 v66, v70, 1
	v_cndmask_b32_e64 v66, 0, v66, s[14:15]
	v_cmp_lt_i32_e64 s[14:15], -1, v94
	v_cmp_gt_f32_e64 s[18:19], v50, v67
	s_and_b64 s[20:21], s[14:15], s[20:21]
	s_or_b64 s[18:19], s[18:19], s[20:21]
	v_cmp_gt_f32_e64 s[20:21], v51, v67
	s_or_b64 s[20:21], s[20:21], s[22:23]
	s_nop 0
	v_cndmask_b32_e64 v74, 0, 1, s[20:21]
	v_addc_co_u32_e64 v74, s[18:19], 0, v74, s[18:19]
	v_cmp_eq_f32_e64 s[20:21], v60, v67
	v_cmp_gt_f32_e64 s[18:19], v60, v67
	s_and_b64 s[20:21], vcc, s[20:21]
	s_or_b64 s[18:19], s[18:19], s[20:21]
	v_cmp_eq_f32_e64 s[20:21], v61, v67
	v_cndmask_b32_e64 v76, 0, 1, s[18:19]
	v_cmp_gt_f32_e64 s[18:19], v61, v67
	s_and_b64 s[20:21], vcc, s[20:21]
	s_or_b64 s[18:19], s[18:19], s[20:21]
	v_addc_co_u32_e64 v74, s[18:19], v74, v76, s[18:19]
	v_cmp_eq_f32_e64 s[20:21], v62, v67
	v_cmp_gt_f32_e64 s[18:19], v62, v67
	s_and_b64 s[20:21], vcc, s[20:21]
	s_or_b64 s[18:19], s[18:19], s[20:21]
	v_cmp_eq_f32_e64 s[20:21], v63, v67
	v_cndmask_b32_e64 v76, 0, 1, s[18:19]
	v_cmp_gt_f32_e64 s[18:19], v63, v67
	s_and_b64 s[20:21], s[0:1], s[20:21]
	s_or_b64 s[18:19], s[18:19], s[20:21]
	v_addc_co_u32_e64 v74, s[18:19], v74, v76, s[18:19]
	v_cmp_eq_f32_e64 s[20:21], v64, v67
	v_cmp_gt_f32_e64 s[18:19], v64, v67
	s_and_b64 s[20:21], s[0:1], s[20:21]
	s_or_b64 s[18:19], s[18:19], s[20:21]
	v_cmp_eq_f32_e64 s[20:21], v65, v67
	v_cndmask_b32_e64 v76, 0, 1, s[18:19]
	v_cmp_gt_f32_e64 s[18:19], v65, v67
	s_and_b64 s[20:21], s[0:1], s[20:21]
	s_or_b64 s[18:19], s[18:19], s[20:21]
	v_addc_co_u32_e64 v74, s[18:19], v74, v76, s[18:19]
	v_cmp_eq_f32_e64 s[20:21], v56, v67
	v_cmp_gt_f32_e64 s[18:19], v56, v67
	s_and_b64 s[20:21], s[0:1], s[20:21]
	s_or_b64 s[18:19], s[18:19], s[20:21]
	v_cmp_eq_f32_e64 s[20:21], v57, v67
	v_cndmask_b32_e64 v76, 0, 1, s[18:19]
	v_cmp_gt_f32_e64 s[18:19], v57, v67
	s_and_b64 s[20:21], s[16:17], s[20:21]
	s_or_b64 s[18:19], s[18:19], s[20:21]
	v_addc_co_u32_e64 v74, s[18:19], v74, v76, s[18:19]
	v_cmp_eq_f32_e64 s[20:21], v58, v67
	v_cmp_gt_f32_e64 s[18:19], v58, v67
	s_and_b64 s[20:21], s[16:17], s[20:21]
	s_or_b64 s[18:19], s[18:19], s[20:21]
	v_cmp_eq_f32_e64 s[20:21], v59, v67
	v_cndmask_b32_e64 v76, 0, 1, s[18:19]
	v_cmp_gt_f32_e64 s[18:19], v59, v67
	s_and_b64 s[20:21], s[16:17], s[20:21]
	s_or_b64 s[18:19], s[18:19], s[20:21]
	v_addc_co_u32_e64 v74, s[18:19], v74, v76, s[18:19]
	v_cmp_eq_f32_e64 s[20:21], v52, v67
	v_cmp_gt_f32_e64 s[18:19], v52, v67
	s_and_b64 s[20:21], s[16:17], s[20:21]
	s_or_b64 s[18:19], s[18:19], s[20:21]
	v_cmp_eq_f32_e64 s[20:21], v53, v67
	v_cndmask_b32_e64 v76, 0, 1, s[18:19]
	v_cmp_gt_f32_e64 s[18:19], v53, v67
	s_and_b64 s[20:21], s[4:5], s[20:21]
	s_or_b64 s[18:19], s[18:19], s[20:21]
	v_addc_co_u32_e64 v74, s[18:19], v74, v76, s[18:19]
	v_cmp_eq_f32_e64 s[20:21], v54, v67
	v_cmp_gt_f32_e64 s[18:19], v54, v67
	s_and_b64 s[20:21], s[4:5], s[20:21]
	s_or_b64 s[18:19], s[18:19], s[20:21]
	v_cmp_eq_f32_e64 s[20:21], v55, v67
	v_cndmask_b32_e64 v76, 0, 1, s[18:19]
	v_cmp_gt_f32_e64 s[18:19], v55, v67
	s_and_b64 s[20:21], s[4:5], s[20:21]
; __device__ __forceinline__ void nsa_item(unsigned char* smem, CP p, int L, int b, int g, int qb, int ocol) {
;     ...
;         for (int mm = 0; mm < 4; ++mm) { const int m = part * 4 + mm; const float v = IMP[q * 33 + m]; int rank = 0;
;             for (int m2 = 0; m2 < 32; ++m2) { const float v2 = IMP[q * 33 + m2]; rank += (v2 > v || (v2 == v && m2 < m)) ? 1 : 0; }
;             if (rank < 8 && v > -INFINITY) bits |= 1u << m; }
	s_or_b64 s[18:19], s[18:19], s[20:21]
	v_addc_co_u32_e64 v74, s[18:19], v74, v76, s[18:19]
	v_cmp_eq_f32_e64 s[20:21], v46, v67
	v_cmp_gt_f32_e64 s[18:19], v46, v67
	s_and_b64 s[20:21], s[4:5], s[20:21]
	s_or_b64 s[18:19], s[18:19], s[20:21]
	v_cmp_eq_f32_e64 s[20:21], v47, v67
	v_cndmask_b32_e64 v76, 0, 1, s[18:19]
	v_cmp_gt_f32_e64 s[18:19], v47, v67
	s_and_b64 s[20:21], s[6:7], s[20:21]
	s_or_b64 s[18:19], s[18:19], s[20:21]
	v_addc_co_u32_e64 v74, s[18:19], v74, v76, s[18:19]
	v_cmp_eq_f32_e64 s[20:21], v48, v67
	v_cmp_gt_f32_e64 s[18:19], v48, v67
	s_and_b64 s[20:21], s[6:7], s[20:21]
	s_or_b64 s[18:19], s[18:19], s[20:21]
	v_cmp_eq_f32_e64 s[20:21], v49, v67
	v_cndmask_b32_e64 v76, 0, 1, s[18:19]
	v_cmp_gt_f32_e64 s[18:19], v49, v67
	s_and_b64 s[20:21], s[6:7], s[20:21]
	s_or_b64 s[18:19], s[18:19], s[20:21]
	v_addc_co_u32_e64 v74, s[18:19], v74, v76, s[18:19]
	v_cmp_eq_f32_e64 s[20:21], v42, v67
	v_cmp_gt_f32_e64 s[18:19], v42, v67
	s_and_b64 s[20:21], s[6:7], s[20:21]
	s_or_b64 s[18:19], s[18:19], s[20:21]
	v_cmp_eq_f32_e64 s[20:21], v43, v67
	v_cndmask_b32_e64 v76, 0, 1, s[18:19]
	v_cmp_gt_f32_e64 s[18:19], v43, v67
	s_and_b64 s[20:21], s[8:9], s[20:21]
	s_or_b64 s[18:19], s[18:19], s[20:21]
	v_addc_co_u32_e64 v74, s[18:19], v74, v76, s[18:19]
	v_cmp_eq_f32_e64 s[20:21], v44, v67
	v_cmp_gt_f32_e64 s[18:19], v44, v67
	s_and_b64 s[20:21], s[8:9], s[20:21]
	s_or_b64 s[18:19], s[18:19], s[20:21]
	v_cmp_eq_f32_e64 s[20:21], v45, v67
	v_cndmask_b32_e64 v76, 0, 1, s[18:19]
	v_cmp_gt_f32_e64 s[18:19], v45, v67
	s_and_b64 s[20:21], s[8:9], s[20:21]
	s_or_b64 s[18:19], s[18:19], s[20:21]
	v_addc_co_u32_e64 v74, s[18:19], v74, v76, s[18:19]
	v_cmp_eq_f32_e64 s[20:21], v38, v67
	v_cmp_gt_f32_e64 s[18:19], v38, v67
	s_and_b64 s[20:21], s[8:9], s[20:21]
	s_or_b64 s[18:19], s[18:19], s[20:21]
	v_cmp_eq_f32_e64 s[20:21], v39, v67
	v_cndmask_b32_e64 v76, 0, 1, s[18:19]
	v_cmp_gt_f32_e64 s[18:19], v39, v67
	s_and_b64 s[20:21], s[10:11], s[20:21]
	s_or_b64 s[18:19], s[18:19], s[20:21]
	v_addc_co_u32_e64 v74, s[18:19], v74, v76, s[18:19]
	v_cmp_eq_f32_e64 s[20:21], v40, v67
	v_cmp_gt_f32_e64 s[18:19], v40, v67
	s_and_b64 s[20:21], s[10:11], s[20:21]
	s_or_b64 s[18:19], s[18:19], s[20:21]
	v_cmp_eq_f32_e64 s[20:21], v41, v67
	v_cndmask_b32_e64 v76, 0, 1, s[18:19]
	v_cmp_gt_f32_e64 s[18:19], v41, v67
	s_and_b64 s[20:21], s[10:11], s[20:21]
	s_or_b64 s[18:19], s[18:19], s[20:21]
	v_addc_co_u32_e64 v74, s[18:19], v74, v76, s[18:19]
	v_cmp_eq_f32_e64 s[20:21], v34, v67
	v_cmp_gt_f32_e64 s[18:19], v34, v67
	s_and_b64 s[20:21], s[10:11], s[20:21]
	s_or_b64 s[18:19], s[18:19], s[20:21]
	v_cmp_eq_f32_e64 s[20:21], v35, v67
	v_cndmask_b32_e64 v76, 0, 1, s[18:19]
	v_cmp_gt_f32_e64 s[18:19], v35, v67
	s_and_b64 s[20:21], s[12:13], s[20:21]
	s_or_b64 s[18:19], s[18:19], s[20:21]
	v_addc_co_u32_e64 v74, s[18:19], v74, v76, s[18:19]
	v_cmp_eq_f32_e64 s[20:21], v36, v67
	v_cmp_gt_f32_e64 s[18:19], v36, v67
	s_and_b64 s[20:21], s[12:13], s[20:21]
	s_or_b64 s[18:19], s[18:19], s[20:21]
	v_cmp_eq_f32_e64 s[20:21], v37, v67
	v_cndmask_b32_e64 v76, 0, 1, s[18:19]
	v_cmp_gt_f32_e64 s[18:19], v37, v67
	s_and_b64 s[20:21], s[12:13], s[20:21]
	s_or_b64 s[18:19], s[18:19], s[20:21]
	v_addc_co_u32_e64 v74, s[18:19], v74, v76, s[18:19]
	v_cmp_gt_u32_e64 s[18:19], 8, v74
	v_cmp_lg_f32_e64 s[20:21], s39, v67
	s_and_b64 s[18:19], s[18:19], s[20:21]
	v_lshlrev_b32_e64 v67, v70, 2
	v_cndmask_b32_e64 v67, 0, v67, s[18:19]
	v_or_b32_e32 v74, v67, v66
	ds_read2_b32 v[66:67], v73 offset0:2 offset1:3
	s_waitcnt lgkmcnt(0)
	v_cmp_eq_f32_e64 s[20:21], v50, v66
	v_cmp_gt_f32_e64 s[18:19], v50, v66
	s_and_b64 s[20:21], s[14:15], s[20:21]
	v_cmp_eq_f32_e64 s[22:23], v51, v66
	s_or_b64 s[18:19], s[18:19], s[20:21]
	v_cmp_gt_f32_e64 s[20:21], v51, v66
	s_and_b64 s[22:23], s[14:15], s[22:23]
	s_or_b64 s[20:21], s[20:21], s[22:23]
	v_cndmask_b32_e64 v73, 0, 1, s[20:21]
	v_addc_co_u32_e64 v73, s[18:19], 0, v73, s[18:19]
	v_cmp_eq_f32_e64 s[20:21], v60, v66
	v_cmp_gt_f32_e64 s[18:19], v60, v66
	s_and_b64 s[20:21], vcc, s[20:21]
	s_or_b64 s[18:19], s[18:19], s[20:21]
	v_cmp_eq_f32_e64 s[20:21], v61, v66
	v_cmp_lt_i32_e64 s[22:23], 3, v72
	v_cndmask_b32_e64 v76, 0, 1, s[18:19]
	v_cmp_gt_f32_e64 s[18:19], v61, v66
	s_and_b64 s[20:21], s[22:23], s[20:21]
	s_or_b64 s[18:19], s[18:19], s[20:21]
	v_addc_co_u32_e64 v73, s[18:19], v73, v76, s[18:19]
	v_cmp_eq_f32_e64 s[20:21], v62, v66
	v_cmp_gt_f32_e64 s[18:19], v62, v66
	s_and_b64 s[20:21], vcc, s[20:21]
	s_or_b64 s[18:19], s[18:19], s[20:21]
	v_cmp_eq_f32_e64 s[20:21], v63, v66
	v_cmp_lt_i32_e64 s[22:23], 5, v72
	v_cndmask_b32_e64 v76, 0, 1, s[18:19]
	v_cmp_gt_f32_e64 s[18:19], v63, v66
	s_and_b64 s[20:21], s[22:23], s[20:21]
	s_or_b64 s[18:19], s[18:19], s[20:21]
	v_addc_co_u32_e64 v73, s[18:19], v73, v76, s[18:19]
	v_cmp_eq_f32_e64 s[20:21], v64, v66
	v_cmp_gt_f32_e64 s[18:19], v64, v66
	s_and_b64 s[20:21], s[0:1], s[20:21]
	s_or_b64 s[18:19], s[18:19], s[20:21]
	v_cmp_eq_f32_e64 s[20:21], v65, v66
	v_cmp_lt_i32_e64 s[22:23], 7, v72
	v_cndmask_b32_e64 v76, 0, 1, s[18:19]
	v_cmp_gt_f32_e64 s[18:19], v65, v66
	s_and_b64 s[20:21], s[22:23], s[20:21]
	s_or_b64 s[18:19], s[18:19], s[20:21]
	v_addc_co_u32_e64 v73, s[18:19], v73, v76, s[18:19]
	v_cmp_eq_f32_e64 s[20:21], v56, v66
	v_cmp_gt_f32_e64 s[18:19], v56, v66
	s_and_b64 s[0:1], s[0:1], s[20:21]
	s_or_b64 s[0:1], s[18:19], s[0:1]
	v_cmp_eq_f32_e64 s[18:19], v57, v66
	v_cmp_lt_i32_e64 s[20:21], 9, v72
	v_cndmask_b32_e64 v76, 0, 1, s[0:1]
	v_cmp_gt_f32_e64 s[0:1], v57, v66
	s_and_b64 s[18:19], s[20:21], s[18:19]
	s_or_b64 s[0:1], s[0:1], s[18:19]
	v_addc_co_u32_e64 v73, s[0:1], v73, v76, s[0:1]
; __device__ __forceinline__ void nsa_item(unsigned char* smem, CP p, int L, int b, int g, int qb, int ocol) {
;     ...
;         for (int mm = 0; mm < 4; ++mm) { const int m = part * 4 + mm; const float v = IMP[q * 33 + m]; int rank = 0;
;             for (int m2 = 0; m2 < 32; ++m2) { const float v2 = IMP[q * 33 + m2]; rank += (v2 > v || (v2 == v && m2 < m)) ? 1 : 0; }
;             if (rank < 8 && v > -INFINITY) bits |= 1u << m; }
	v_cmp_eq_f32_e64 s[18:19], v58, v66
	v_cmp_gt_f32_e64 s[0:1], v58, v66
	s_and_b64 s[18:19], s[16:17], s[18:19]
	s_or_b64 s[0:1], s[0:1], s[18:19]
	v_cmp_eq_f32_e64 s[18:19], v59, v66
	v_cmp_lt_i32_e64 s[20:21], 11, v72
	v_cndmask_b32_e64 v76, 0, 1, s[0:1]
	v_cmp_gt_f32_e64 s[0:1], v59, v66
	s_and_b64 s[18:19], s[20:21], s[18:19]
	s_or_b64 s[0:1], s[0:1], s[18:19]
	v_addc_co_u32_e64 v73, s[0:1], v73, v76, s[0:1]
	v_cmp_eq_f32_e64 s[18:19], v52, v66
	v_cmp_gt_f32_e64 s[0:1], v52, v66
	s_and_b64 s[16:17], s[16:17], s[18:19]
	s_or_b64 s[0:1], s[0:1], s[16:17]
	v_cmp_eq_f32_e64 s[16:17], v53, v66
	v_cmp_lt_i32_e64 s[18:19], 13, v72
	v_cndmask_b32_e64 v76, 0, 1, s[0:1]
	v_cmp_gt_f32_e64 s[0:1], v53, v66
	s_and_b64 s[16:17], s[18:19], s[16:17]
	s_or_b64 s[0:1], s[0:1], s[16:17]
	v_addc_co_u32_e64 v73, s[0:1], v73, v76, s[0:1]
	v_cmp_eq_f32_e64 s[16:17], v54, v66
	v_cmp_gt_f32_e64 s[0:1], v54, v66
	s_and_b64 s[16:17], s[4:5], s[16:17]
	s_or_b64 s[0:1], s[0:1], s[16:17]
	v_cmp_eq_f32_e64 s[16:17], v55, v66
	v_cmp_lt_i32_e64 s[18:19], 15, v72
	v_cndmask_b32_e64 v76, 0, 1, s[0:1]
	v_cmp_gt_f32_e64 s[0:1], v55, v66
	s_and_b64 s[16:17], s[18:19], s[16:17]
	s_or_b64 s[0:1], s[0:1], s[16:17]
	v_addc_co_u32_e64 v73, s[0:1], v73, v76, s[0:1]
	v_cmp_eq_f32_e64 s[16:17], v46, v66
	v_cmp_gt_f32_e64 s[0:1], v46, v66
	s_and_b64 s[4:5], s[4:5], s[16:17]
	s_or_b64 s[0:1], s[0:1], s[4:5]
	v_cmp_eq_f32_e64 s[4:5], v47, v66
	v_cmp_lt_i32_e64 s[16:17], 17, v72
	v_cndmask_b32_e64 v76, 0, 1, s[0:1]
	v_cmp_gt_f32_e64 s[0:1], v47, v66
	s_and_b64 s[4:5], s[16:17], s[4:5]
	s_or_b64 s[0:1], s[0:1], s[4:5]
	v_addc_co_u32_e64 v73, s[0:1], v73, v76, s[0:1]
	v_cmp_eq_f32_e64 s[4:5], v48, v66
	v_cmp_gt_f32_e64 s[0:1], v48, v66
	s_and_b64 s[4:5], s[6:7], s[4:5]
	s_or_b64 s[0:1], s[0:1], s[4:5]
	v_cmp_eq_f32_e64 s[4:5], v49, v66
	v_cmp_lt_i32_e64 s[16:17], 19, v72
	v_cndmask_b32_e64 v76, 0, 1, s[0:1]
	v_cmp_gt_f32_e64 s[0:1], v49, v66
	s_and_b64 s[4:5], s[16:17], s[4:5]
	s_or_b64 s[0:1], s[0:1], s[4:5]
	v_addc_co_u32_e64 v73, s[0:1], v73, v76, s[0:1]
	v_cmp_eq_f32_e64 s[4:5], v42, v66
	v_cmp_gt_f32_e64 s[0:1], v42, v66
	s_and_b64 s[4:5], s[6:7], s[4:5]
	s_or_b64 s[0:1], s[0:1], s[4:5]
	v_cmp_eq_f32_e64 s[4:5], v43, v66
	v_cmp_lt_i32_e64 s[6:7], 21, v72
	v_cndmask_b32_e64 v76, 0, 1, s[0:1]
	v_cmp_gt_f32_e64 s[0:1], v43, v66
	s_and_b64 s[4:5], s[6:7], s[4:5]
	s_or_b64 s[0:1], s[0:1], s[4:5]
	v_addc_co_u32_e64 v73, s[0:1], v73, v76, s[0:1]
	v_cmp_eq_f32_e64 s[4:5], v44, v66
	v_cmp_gt_f32_e64 s[0:1], v44, v66
	s_and_b64 s[4:5], s[8:9], s[4:5]
	s_or_b64 s[0:1], s[0:1], s[4:5]
	v_cmp_eq_f32_e64 s[4:5], v45, v66
	v_cmp_lt_i32_e64 s[6:7], 23, v72
	v_cndmask_b32_e64 v76, 0, 1, s[0:1]
	v_cmp_gt_f32_e64 s[0:1], v45, v66
	s_and_b64 s[4:5], s[6:7], s[4:5]
	s_or_b64 s[0:1], s[0:1], s[4:5]
	v_addc_co_u32_e64 v73, s[0:1], v73, v76, s[0:1]
	v_cmp_eq_f32_e64 s[4:5], v38, v66
	v_cmp_gt_f32_e64 s[0:1], v38, v66
	s_and_b64 s[4:5], s[8:9], s[4:5]
	s_or_b64 s[0:1], s[0:1], s[4:5]
	v_cmp_eq_f32_e64 s[4:5], v39, v66
	v_cmp_lt_i32_e64 s[6:7], 25, v72
	v_cndmask_b32_e64 v76, 0, 1, s[0:1]
	v_cmp_gt_f32_e64 s[0:1], v39, v66
	s_and_b64 s[4:5], s[6:7], s[4:5]
	s_or_b64 s[0:1], s[0:1], s[4:5]
	v_addc_co_u32_e64 v73, s[0:1], v73, v76, s[0:1]
	v_cmp_eq_f32_e64 s[4:5], v40, v66
	v_cmp_gt_f32_e64 s[0:1], v40, v66
	s_and_b64 s[4:5], s[10:11], s[4:5]
	s_or_b64 s[0:1], s[0:1], s[4:5]
	v_cmp_eq_f32_e64 s[4:5], v41, v66
	v_cmp_lt_i32_e64 s[6:7], 27, v72
	v_cndmask_b32_e64 v76, 0, 1, s[0:1]
	v_cmp_gt_f32_e64 s[0:1], v41, v66
	s_and_b64 s[4:5], s[6:7], s[4:5]
	s_or_b64 s[0:1], s[0:1], s[4:5]
	v_addc_co_u32_e64 v73, s[0:1], v73, v76, s[0:1]
	v_cmp_eq_f32_e64 s[4:5], v34, v66
	v_cmp_gt_f32_e64 s[0:1], v34, v66
	s_and_b64 s[4:5], s[10:11], s[4:5]
	s_or_b64 s[0:1], s[0:1], s[4:5]
	v_cmp_eq_f32_e64 s[4:5], v35, v66
	v_cmp_lt_i32_e64 s[6:7], 29, v72
	v_cndmask_b32_e64 v76, 0, 1, s[0:1]
	v_cmp_gt_f32_e64 s[0:1], v35, v66
	s_and_b64 s[4:5], s[6:7], s[4:5]
	s_or_b64 s[0:1], s[0:1], s[4:5]
	v_addc_co_u32_e64 v73, s[0:1], v73, v76, s[0:1]
	v_cmp_eq_f32_e64 s[4:5], v36, v66
	v_cmp_gt_f32_e64 s[0:1], v36, v66
	s_and_b64 s[4:5], s[12:13], s[4:5]
	s_or_b64 s[0:1], s[0:1], s[4:5]
	v_cmp_eq_f32_e64 s[4:5], v37, v66
	v_cmp_lt_i32_e64 s[6:7], 31, v72
	v_cndmask_b32_e64 v76, 0, 1, s[0:1]
	v_cmp_gt_f32_e64 s[0:1], v37, v66
	s_and_b64 s[4:5], s[6:7], s[4:5]
	s_or_b64 s[0:1], s[0:1], s[4:5]
	v_addc_co_u32_e64 v72, s[0:1], v73, v76, s[0:1]
	v_cmp_gt_u32_e64 s[0:1], 8, v72
	v_cmp_lg_f32_e64 s[4:5], s39, v66
	s_and_b64 s[0:1], s[0:1], s[4:5]
	v_lshlrev_b32_e64 v66, v70, 4
	v_cmp_eq_f32_e64 s[4:5], v50, v67
	v_cndmask_b32_e64 v66, 0, v66, s[0:1]
	v_cmp_gt_f32_e64 s[0:1], v50, v67
	s_and_b64 s[4:5], s[14:15], s[4:5]
	v_cmp_eq_f32_e64 s[6:7], v51, v67
	s_or_b64 s[0:1], s[0:1], s[4:5]
	v_cmp_gt_f32_e64 s[4:5], v51, v67
	s_and_b64 s[6:7], s[14:15], s[6:7]
	s_or_b64 s[4:5], s[4:5], s[6:7]
	v_cndmask_b32_e64 v50, 0, 1, s[4:5]
	v_addc_co_u32_e64 v50, s[0:1], 0, v50, s[0:1]
	v_cmp_eq_f32_e64 s[4:5], v60, v67
	v_cmp_gt_f32_e64 s[0:1], v60, v67
	s_and_b64 s[4:5], s[14:15], s[4:5]
	s_or_b64 s[0:1], s[0:1], s[4:5]
	v_cmp_eq_f32_e64 s[4:5], v61, v67
	v_cndmask_b32_e64 v51, 0, 1, s[0:1]
	v_cmp_gt_f32_e64 s[0:1], v61, v67
	s_and_b64 s[4:5], vcc, s[4:5]
	s_or_b64 vcc, s[0:1], s[4:5]
	v_addc_co_u32_e32 v50, vcc, v50, v51, vcc
	v_cmp_eq_f32_e64 s[0:1], v62, v67
	v_cmp_lt_i32_e64 s[4:5], 4, v71
	v_cmp_gt_f32_e32 vcc, v62, v67
	s_and_b64 s[0:1], s[4:5], s[0:1]
	s_or_b64 s[0:1], vcc, s[0:1]
	v_cndmask_b32_e64 v51, 0, 1, s[0:1]
	v_cmp_eq_f32_e64 s[0:1], v63, v67
	v_cmp_lt_i32_e64 s[4:5], 5, v71
	v_cmp_gt_f32_e32 vcc, v63, v67
	s_and_b64 s[0:1], s[4:5], s[0:1]
; __device__ __forceinline__ void nsa_item(unsigned char* smem, CP p, int L, int b, int g, int qb, int ocol) {
;     ...
;         for (int mm = 0; mm < 4; ++mm) { const int m = part * 4 + mm; const float v = IMP[q * 33 + m]; int rank = 0;
;             for (int m2 = 0; m2 < 32; ++m2) { const float v2 = IMP[q * 33 + m2]; rank += (v2 > v || (v2 == v && m2 < m)) ? 1 : 0; }
;             if (rank < 8 && v > -INFINITY) bits |= 1u << m; }
;         atomicOr(&SELM[q], bits); atomicOr(ORM, bits);
;     }
;     __syncthreads();
;     const unsigned mysel = SELM[ql], orm = *ORM;
	s_or_b64 vcc, vcc, s[0:1]
	v_addc_co_u32_e32 v50, vcc, v50, v51, vcc
	v_cmp_eq_f32_e64 s[0:1], v64, v67
	v_cmp_lt_i32_e64 s[4:5], 6, v71
	v_cmp_gt_f32_e32 vcc, v64, v67
	s_and_b64 s[0:1], s[4:5], s[0:1]
	s_or_b64 s[0:1], vcc, s[0:1]
	v_cndmask_b32_e64 v51, 0, 1, s[0:1]
	v_cmp_eq_f32_e64 s[0:1], v65, v67
	v_cmp_lt_i32_e64 s[4:5], 7, v71
	v_cmp_gt_f32_e32 vcc, v65, v67
	s_and_b64 s[0:1], s[4:5], s[0:1]
	s_or_b64 vcc, vcc, s[0:1]
	v_addc_co_u32_e32 v50, vcc, v50, v51, vcc
	v_cmp_eq_f32_e64 s[0:1], v56, v67
	v_cmp_lt_i32_e64 s[4:5], 8, v71
	v_cmp_gt_f32_e32 vcc, v56, v67
	s_and_b64 s[0:1], s[4:5], s[0:1]
	s_or_b64 s[0:1], vcc, s[0:1]
	v_cndmask_b32_e64 v51, 0, 1, s[0:1]
	v_cmp_eq_f32_e64 s[0:1], v57, v67
	v_cmp_lt_i32_e64 s[4:5], 9, v71
	v_cmp_gt_f32_e32 vcc, v57, v67
	s_and_b64 s[0:1], s[4:5], s[0:1]
	s_or_b64 vcc, vcc, s[0:1]
	v_addc_co_u32_e32 v50, vcc, v50, v51, vcc
	v_cmp_eq_f32_e64 s[0:1], v58, v67
	v_cmp_lt_i32_e64 s[4:5], 10, v71
	v_cmp_gt_f32_e32 vcc, v58, v67
	s_and_b64 s[0:1], s[4:5], s[0:1]
	s_or_b64 s[0:1], vcc, s[0:1]
	v_cndmask_b32_e64 v51, 0, 1, s[0:1]
	v_cmp_eq_f32_e64 s[0:1], v59, v67
	v_cmp_lt_i32_e64 s[4:5], 11, v71
	v_cmp_gt_f32_e32 vcc, v59, v67
	s_and_b64 s[0:1], s[4:5], s[0:1]
	s_or_b64 vcc, vcc, s[0:1]
	v_addc_co_u32_e32 v50, vcc, v50, v51, vcc
	v_cmp_eq_f32_e64 s[0:1], v52, v67
	v_cmp_lt_i32_e64 s[4:5], 12, v71
	v_cmp_gt_f32_e32 vcc, v52, v67
	s_and_b64 s[0:1], s[4:5], s[0:1]
	s_or_b64 s[0:1], vcc, s[0:1]
	v_cndmask_b32_e64 v51, 0, 1, s[0:1]
	v_cmp_eq_f32_e64 s[0:1], v53, v67
	v_cmp_lt_i32_e64 s[4:5], 13, v71
	v_cmp_gt_f32_e32 vcc, v53, v67
	s_and_b64 s[0:1], s[4:5], s[0:1]
	s_or_b64 vcc, vcc, s[0:1]
	v_addc_co_u32_e32 v50, vcc, v50, v51, vcc
	v_cmp_eq_f32_e64 s[0:1], v54, v67
	v_cmp_lt_i32_e64 s[4:5], 14, v71
	v_cmp_gt_f32_e32 vcc, v54, v67
	s_and_b64 s[0:1], s[4:5], s[0:1]
	s_or_b64 s[0:1], vcc, s[0:1]
	v_cndmask_b32_e64 v51, 0, 1, s[0:1]
	v_cmp_eq_f32_e64 s[0:1], v55, v67
	v_cmp_lt_i32_e64 s[4:5], 15, v71
	v_cmp_gt_f32_e32 vcc, v55, v67
	s_and_b64 s[0:1], s[4:5], s[0:1]
	s_or_b64 vcc, vcc, s[0:1]
	v_addc_co_u32_e32 v50, vcc, v50, v51, vcc
	v_cmp_eq_f32_e64 s[0:1], v46, v67
	v_cmp_lt_i32_e64 s[4:5], 16, v71
	v_cmp_gt_f32_e32 vcc, v46, v67
	s_and_b64 s[0:1], s[4:5], s[0:1]
	s_or_b64 s[0:1], vcc, s[0:1]
	v_cndmask_b32_e64 v46, 0, 1, s[0:1]
	v_cmp_eq_f32_e64 s[0:1], v47, v67
	v_cmp_lt_i32_e64 s[4:5], 17, v71
	v_cmp_gt_f32_e32 vcc, v47, v67
	s_and_b64 s[0:1], s[4:5], s[0:1]
	s_or_b64 vcc, vcc, s[0:1]
	v_addc_co_u32_e32 v46, vcc, v50, v46, vcc
	v_cmp_eq_f32_e64 s[0:1], v48, v67
	v_cmp_lt_i32_e64 s[4:5], 18, v71
	v_cmp_gt_f32_e32 vcc, v48, v67
	s_and_b64 s[0:1], s[4:5], s[0:1]
	s_or_b64 s[0:1], vcc, s[0:1]
	v_cndmask_b32_e64 v47, 0, 1, s[0:1]
	v_cmp_eq_f32_e64 s[0:1], v49, v67
	v_cmp_lt_i32_e64 s[4:5], 19, v71
	v_cmp_gt_f32_e32 vcc, v49, v67
	s_and_b64 s[0:1], s[4:5], s[0:1]
	s_or_b64 vcc, vcc, s[0:1]
	v_addc_co_u32_e32 v46, vcc, v46, v47, vcc
	v_cmp_eq_f32_e64 s[0:1], v42, v67
	v_cmp_lt_i32_e64 s[4:5], 20, v71
	v_cmp_gt_f32_e32 vcc, v42, v67
	s_and_b64 s[0:1], s[4:5], s[0:1]
	s_or_b64 s[0:1], vcc, s[0:1]
	v_cndmask_b32_e64 v42, 0, 1, s[0:1]
	v_cmp_eq_f32_e64 s[0:1], v43, v67
	v_cmp_lt_i32_e64 s[4:5], 21, v71
	v_cmp_gt_f32_e32 vcc, v43, v67
	s_and_b64 s[0:1], s[4:5], s[0:1]
	s_or_b64 vcc, vcc, s[0:1]
	v_addc_co_u32_e32 v42, vcc, v46, v42, vcc
	v_cmp_eq_f32_e64 s[0:1], v44, v67
	v_cmp_lt_i32_e64 s[4:5], 22, v71
	v_cmp_gt_f32_e32 vcc, v44, v67
	s_and_b64 s[0:1], s[4:5], s[0:1]
	s_or_b64 s[0:1], vcc, s[0:1]
	v_cndmask_b32_e64 v43, 0, 1, s[0:1]
	v_cmp_eq_f32_e64 s[0:1], v45, v67
	v_cmp_lt_i32_e64 s[4:5], 23, v71
	v_cmp_gt_f32_e32 vcc, v45, v67
	s_and_b64 s[0:1], s[4:5], s[0:1]
	s_or_b64 vcc, vcc, s[0:1]
	v_addc_co_u32_e32 v42, vcc, v42, v43, vcc
	v_cmp_eq_f32_e64 s[0:1], v38, v67
	v_cmp_lt_i32_e64 s[4:5], 24, v71
	v_cmp_gt_f32_e32 vcc, v38, v67
	s_and_b64 s[0:1], s[4:5], s[0:1]
	s_or_b64 s[0:1], vcc, s[0:1]
	v_cndmask_b32_e64 v38, 0, 1, s[0:1]
	v_cmp_eq_f32_e64 s[0:1], v39, v67
	v_cmp_lt_i32_e64 s[4:5], 25, v71
	v_cmp_gt_f32_e32 vcc, v39, v67
	s_and_b64 s[0:1], s[4:5], s[0:1]
	s_or_b64 vcc, vcc, s[0:1]
	v_addc_co_u32_e32 v38, vcc, v42, v38, vcc
	v_cmp_eq_f32_e64 s[0:1], v40, v67
	v_cmp_lt_i32_e64 s[4:5], 26, v71
	v_cmp_gt_f32_e32 vcc, v40, v67
	s_and_b64 s[0:1], s[4:5], s[0:1]
	s_or_b64 s[0:1], vcc, s[0:1]
	v_cndmask_b32_e64 v39, 0, 1, s[0:1]
	v_cmp_eq_f32_e64 s[0:1], v41, v67
	v_cmp_lt_i32_e64 s[4:5], 27, v71
	v_cmp_gt_f32_e32 vcc, v41, v67
	s_and_b64 s[0:1], s[4:5], s[0:1]
	s_or_b64 vcc, vcc, s[0:1]
	v_addc_co_u32_e32 v38, vcc, v38, v39, vcc
	v_cmp_eq_f32_e64 s[0:1], v34, v67
	v_cmp_lt_i32_e64 s[4:5], 28, v71
	v_cmp_gt_f32_e32 vcc, v34, v67
	s_and_b64 s[0:1], s[4:5], s[0:1]
	s_or_b64 s[0:1], vcc, s[0:1]
	v_cndmask_b32_e64 v34, 0, 1, s[0:1]
	v_cmp_eq_f32_e64 s[0:1], v35, v67
	v_cmp_lt_i32_e64 s[4:5], 29, v71
	v_cmp_gt_f32_e32 vcc, v35, v67
	s_and_b64 s[0:1], s[4:5], s[0:1]
	s_or_b64 vcc, vcc, s[0:1]
	v_addc_co_u32_e32 v34, vcc, v38, v34, vcc
	v_cmp_eq_f32_e64 s[0:1], v36, v67
	v_cmp_lt_i32_e64 s[4:5], 30, v71
	v_cmp_gt_f32_e32 vcc, v36, v67
	s_and_b64 s[0:1], s[4:5], s[0:1]
	s_or_b64 s[0:1], vcc, s[0:1]
	v_cndmask_b32_e64 v35, 0, 1, s[0:1]
	v_cmp_eq_f32_e64 s[0:1], v37, v67
	v_cmp_lt_i32_e64 s[4:5], 31, v71
	v_cmp_gt_f32_e32 vcc, v37, v67
	s_and_b64 s[0:1], s[4:5], s[0:1]
	s_or_b64 vcc, vcc, s[0:1]
	v_addc_co_u32_e32 v34, vcc, v34, v35, vcc
	v_cmp_gt_u32_e32 vcc, 8, v34
	v_cmp_lg_f32_e64 s[0:1], s39, v67
	s_and_b64 vcc, vcc, s[0:1]
	v_lshlrev_b32_e64 v34, v70, 8
	v_cndmask_b32_e32 v34, 0, v34, vcc
	v_or3_b32 v34, v74, v66, v34
	v_lshl_add_u32 v35, v96, 2, 0
	ds_or_b32 v35, v34 offset:20736
	s_nop 0
	v_or_b32_dpp v35, v34, v34 quad_perm:[1,0,3,2] row_mask:0xf bank_mask:0xf bound_ctrl:1
	s_nop 1
	v_or_b32_dpp v35, v35, v35 quad_perm:[2,3,0,1] row_mask:0xf bank_mask:0xf bound_ctrl:1
	s_nop 1
	v_or_b32_dpp v35, v35, v35 row_half_mirror row_mask:0xf bank_mask:0xf bound_ctrl:1
	s_nop 1
	v_or_b32_dpp v35, v35, v35 row_mirror row_mask:0xf bank_mask:0xf bound_ctrl:1
	s_nop 1
	v_readlane_b32 s0, v35, 0
	v_readlane_b32 s1, v35, 16
	v_readlane_b32 s4, v35, 32
	v_readlane_b32 s5, v35, 48
	s_or_b32 s0, s0, s1
	s_or_b32 s4, s4, s5
	s_or_b32 s0, s0, s4
	s_or_b32 s38, s38, s0
	v_mbcnt_lo_u32_b32 v34, exec_lo, 0
	v_mbcnt_hi_u32_b32 v34, exec_hi, v34
	v_cmp_eq_u32_e32 vcc, 0, v34
	s_and_saveexec_b64 s[0:1], vcc
	s_xor_b64 s[0:1], exec, s[0:1]
	v_mov_b32_e32 v34, s38
	ds_or_b32 v1, v34 offset:20992
	s_or_b64 exec, exec, s[0:1]
	v_mul_f32_e32 v44, v69, v68
	v_pk_mul_f32 v[52:53], v[2:3], v[44:45] op_sel_hi:[1,0]
	v_lshl_add_u32 v2, v95, 2, 0
	s_waitcnt lgkmcnt(0)
	s_barrier
; DI int tid_() { int t = threadIdx.x; asm volatile("" : "+v"(t)); return t; }
; DI void kv_fetch(KVRegs& r, const bf16_t* pb, int kcol, int vcol, int k0) {
;     const int tid = tid_();
;     const unsigned ok_ = (unsigned)((k0 + (tid >> 3)) * PLD + kcol + (tid & 7) * 8) * 2u, ov_ = (unsigned)((k0 + (tid & 63)) * PLD + vcol + (tid >> 6) * 8) * 2u;
;     r.k = *(const u32x4*)((const char*)pb + ok_);
;     r.v = *(const u32x4*)((const char*)pb + ov_);
; }
; DI void kv_store(const KVRegs& r, bf16_t* KT, bf16_t* VT) {
;     const int tid = tid_();
;     *(u32x4*)(KT + (tid >> 3) * KTS + (tid & 7) * 8) = r.k;
;     const int key = tid & 63, ch = tid >> 6;
; #pragma unroll
;     for (int j = 0; j < 8; ++j) VT[(ch * 8 + j) * KTS + key] = (bf16_t)((j & 1) ? (r.v[j >> 1] >> 16) : (r.v[j >> 1] & 0xFFFFu));
; }
; __device__ __forceinline__ void nsa_item(unsigned char* smem, CP p, int L, int b, int g, int qb, int ocol) {
;     ...
;     const unsigned mysel = SELM[ql], orm = *ORM;
;     __syncthreads();
;     float* PARK = PA + (wv * 32) * 64 + lane;
; #pragma unroll
;     for (int i = 0; i < 16; ++i) { PARK[i * 64] = fin0[i]; PARK[(16 + i) * 64] = fin1[i]; }
;     {
;         FlashState st;
; #pragma unroll
;         for (int i = 0; i < 16; ++i) { st.o0[i] = 0.f; st.o1[i] = 0.f; }
;         st.m = -INFINITY; st.l = 0.f;
;         const unsigned todo = orm & (qb >= 31 ? 0xFFFFFFFFu : ((2u << qb) - 1u));
;         KVRegs kr;
;         int m = todo ? __builtin_ctz(todo) : -1;
;         if (m >= 0) { kv_fetch(kr, pb, C_KS + g * 64, C_VS + g * 64, m * 64); __syncthreads(); kv_store(kr, KT, VT); __syncthreads(); }
	ds_read_b32 v141, v2 offset:20736
	ds_read_b32 v2, v1 offset:20992
	v_lshlrev_b32_e32 v3, 13, v94
	v_add3_u32 v151, 0, v3, v0
	v_lshl_add_u32 v0, 2, v75, -1
	v_cmp_lt_u32_e32 vcc, 31, v130
	v_pk_mul_f32 v[32:33], v[32:33], v[44:45] op_sel_hi:[1,0]
	v_pk_mul_f32 v[30:31], v[30:31], v[44:45] op_sel_hi:[1,0]
	v_cndmask_b32_e32 v0, -1, v0, vcc
	s_waitcnt lgkmcnt(0)
	v_and_b32_e32 v142, v2, v0
	v_pk_mul_f32 v[28:29], v[28:29], v[44:45] op_sel_hi:[1,0]
	v_pk_mul_f32 v[34:35], v[26:27], v[44:45] op_sel_hi:[1,0]
	v_pk_mul_f32 v[36:37], v[24:25], v[44:45] op_sel_hi:[1,0]
	v_pk_mul_f32 v[38:39], v[22:23], v[44:45] op_sel_hi:[1,0]
	v_pk_mul_f32 v[40:41], v[20:21], v[44:45] op_sel_hi:[1,0]
	v_pk_mul_f32 v[42:43], v[18:19], v[44:45] op_sel_hi:[1,0]
	v_pk_mul_f32 v[16:17], v[16:17], v[44:45] op_sel_hi:[1,0]
	v_pk_mul_f32 v[14:15], v[14:15], v[44:45] op_sel_hi:[1,0]
	v_pk_mul_f32 v[12:13], v[12:13], v[44:45] op_sel_hi:[1,0]
	v_pk_mul_f32 v[60:61], v[10:11], v[44:45] op_sel_hi:[1,0]
	v_pk_mul_f32 v[58:59], v[8:9], v[44:45] op_sel_hi:[1,0]
	v_pk_mul_f32 v[56:57], v[6:7], v[44:45] op_sel_hi:[1,0]
	v_pk_mul_f32 v[54:55], v[4:5], v[44:45] op_sel_hi:[1,0]
	v_cmp_ne_u32_e32 vcc, 0, v142
	v_lshlrev_b32_e32 v137, 6, v77
	v_mul_u32_u24_e32 v138, 0x48, v132
	v_sub_u32_e32 v139, 0, v134
	s_barrier
	ds_write2st64_b32 v151, v52, v53 offset0:84 offset1:85
	ds_write2st64_b32 v151, v42, v43 offset0:100 offset1:101
	ds_write2st64_b32 v151, v54, v55 offset0:86 offset1:87
	ds_write2st64_b32 v151, v40, v41 offset0:102 offset1:103
	ds_write2st64_b32 v151, v56, v57 offset0:88 offset1:89
	ds_write2st64_b32 v151, v38, v39 offset0:104 offset1:105
	ds_write2st64_b32 v151, v58, v59 offset0:90 offset1:91
	ds_write2st64_b32 v151, v36, v37 offset0:106 offset1:107
	ds_write2st64_b32 v151, v60, v61 offset0:92 offset1:93
	ds_write2st64_b32 v151, v34, v35 offset0:108 offset1:109
	ds_write2st64_b32 v151, v12, v13 offset0:94 offset1:95
	ds_write2st64_b32 v151, v28, v29 offset0:110 offset1:111
	ds_write2st64_b32 v151, v14, v15 offset0:96 offset1:97
	ds_write2st64_b32 v151, v30, v31 offset0:112 offset1:113
	ds_write2st64_b32 v151, v16, v17 offset0:98 offset1:99
	ds_write2st64_b32 v151, v32, v33 offset0:114 offset1:115
	s_and_saveexec_b64 s[0:1], vcc
	s_xor_b64 s[4:5], exec, s[0:1]
	s_cbranch_execz .LBB0_785
	v_ffbl_b32_e32 v154, v142
	v_mov_b32_e32 v3, v238
	v_lshlrev_b32_e32 v2, 6, v154
	v_or_b32_e32 v143, 0xb00, v137
	v_ashrrev_i32_e32 v4, 3, v3
	v_add_u32_e32 v0, v4, v2
	s_movk_i32 s0, 0x2100
	v_lshlrev_b32_e32 v5, 3, v3
	v_mul_lo_u32 v0, v0, s0
	v_and_or_b32 v5, v5, 56, v143
	v_or_b32_e32 v144, 0xb80, v137
	v_add_lshl_u32 v0, v5, v0, 1
	v_and_or_b32 v2, v3, 63, v2
	v_and_b32_e32 v3, 0x7ffffff8, v4
	v_mul_u32_u24_e32 v2, 0x2100, v2
	v_add_u32_e32 v3, v3, v144
	v_lshl_add_u64 v[4:5], v[126:127], 0, v[0:1]
	v_add_lshl_u32 v2, v3, v2, 1
	global_load_dwordx4 v[114:117], v[4:5], off
	v_mov_b32_e32 v3, v1
	v_lshl_add_u64 v[2:3], v[126:127], 0, v[2:3]
	global_load_dwordx4 v[118:121], v[2:3], off
	v_mov_b32_e32 v0, v238
	s_waitcnt lgkmcnt(0)
	s_barrier
	v_mul_u32_u24_e32 v138, 0x48, v132
	v_ashrrev_i32_e32 v4, 3, v0
	v_lshlrev_b32_e32 v3, 4, v0
	v_mul_lo_u32 v2, v4, s74
	v_and_b32_e32 v3, 0x70, v3
	v_add3_u32 v2, 0, v2, v3
	v_and_b32_e32 v0, 63, v0
	v_lshl_add_u32 v0, v0, 1, 0
	v_mov_b32_e32 v140, 0
	v_sub_u32_e32 v145, 28, v131
	v_sub_u32_e32 v139, 0, v134
	v_mov_b32_e32 v152, 0xff800000
	s_mov_b64 s[6:7], 0
	v_mov_b32_e32 v18, 0
	v_mov_b32_e32 v19, v140
	v_mov_b32_e32 v20, v140
	v_mov_b32_e32 v21, v140
	v_mov_b32_e32 v22, v140
	v_mov_b32_e32 v23, v140
	v_mov_b32_e32 v24, v140
	v_mov_b32_e32 v25, v140
	v_mov_b32_e32 v26, v140
	v_mov_b32_e32 v27, v140
	v_mov_b32_e32 v28, v140
	v_mov_b32_e32 v29, v140
	v_mov_b32_e32 v30, v140
	v_mov_b32_e32 v31, v140
	v_mov_b32_e32 v32, v140
	v_mov_b32_e32 v33, v140
	v_mov_b32_e32 v5, v140
	v_mov_b32_e32 v6, v140
	v_mov_b32_e32 v7, v140
	v_mov_b32_e32 v8, v140
	v_mov_b32_e32 v9, v140
	v_mov_b32_e32 v10, v140
	v_mov_b32_e32 v11, v140
	v_mov_b32_e32 v12, v140
	v_mov_b32_e32 v13, v140
	v_mov_b32_e32 v14, v140
	v_mov_b32_e32 v15, v140
	v_mov_b32_e32 v16, v140
	v_mov_b32_e32 v17, v140
	s_waitcnt vmcnt(1)
	ds_write_b128 v2, v[114:117]
	v_and_b32_e32 v2, 0xffffff8, v4
	v_mad_u64_u32 v[2:3], s[0:1], v2, s74, v[0:1]
	s_waitcnt vmcnt(0)
	ds_write_b16 v2, v118 offset:9216
	ds_write_b16_d16_hi v2, v118 offset:9360
	ds_write_b16 v2, v119 offset:9504
	ds_write_b16_d16_hi v2, v119 offset:9648
	ds_write_b16 v2, v120 offset:9792
	ds_write_b16_d16_hi v2, v120 offset:9936
	ds_write_b16 v2, v121 offset:10080
	v_or_b32_e32 v2, 7, v4
	v_mad_u64_u32 v[2:3], s[0:1], v2, s74, v[0:1]
	v_lshl_add_u32 v0, v138, 1, 0
	ds_write_b16_d16_hi v2, v121 offset:9216
	v_lshl_add_u32 v146, v134, 1, v0
	v_lshl_add_u32 v147, v148, 1, v0
	v_mov_b32_e32 v2, 0
	v_mov_b32_e32 v3, v140
	v_mov_b32_e32 v4, v140
	s_waitcnt lgkmcnt(0)
	s_barrier
	s_branch .LBB0_774
